# attention: lazy lane-half exchange, PV/QK MFMAs not interleaved, no static priority raise for waves 4-7 - chosen with the 4x-repeated-phase A/B amplifier
# speedup vs baseline: 1.0131x; 1.0082x over previous
; #define AT_GLOADK(k0) do { kreg = *(const u32x4*)(Kb + (size_t)((k0) + (tid >> 3)) * 64 + (tid & 7) * 8); \
;             if (MLA) preg = *(const u32x2*)(Pb + (size_t)((k0) + (tid >> 3)) * 32 + (tid & 7) * 4); } while (0)
; #define AT_GLOADV(k0) do { vreg = *(const u32x4*)(Vb + (size_t)((k0) + (tid >> 3)) * 64 + (tid & 7) * 8); } while (0)
; #define AT_WRITEK(buf) do { *(LAS u32x4*)(lds + (buf) * KBUF + (tid >> 3) * KSTR + (tid & 7) * 16) = kreg; \
;             if (MLA) *(LAS u32x2*)(lds + (buf) * KBUF + (tid >> 3) * KSTR + 128 + (tid & 7) * 8) = preg; } while (0)
; #define AT_WRITEV(buf) do { *(LAS u32x4*)(lds + 2 * KBUF + (buf) * VBUF + (tid >> 3) * VSTR + (tid & 7) * 16) = vreg; } while (0)
; template <bool MLA>
; DI void attn_phase(const int TID, const int BID, LAS unsigned char* lds, const Params& p, bool need_ctx) {
;     ...
;         f32x16 o0, o1, sa0, sa1, sb0, sb1;
; #pragma unroll
;         for (int j = 0; j < 16; ++j) { o0[j] = 0.f; o1[j] = 0.f; }
;         float mrun = -1e30f, lsum = 0.f;
;         if (wid >= 4) __builtin_amdgcn_s_setprio(1);
;         const int ntile = nk >> 6;
;         AT_GLOADK(0); AT_GLOADV(0); AT_WRITEK(0); AT_WRITEV(0);
;         AT_GLOADK(64); AT_WRITEK(1);
;         __syncthreads();
;         AT_QK(sa0, sa1, 0);
;         __syncthreads();
.Lamla_item:
	s_mov_b32 s52, 0x3000
	s_mov_b32 s53, 0x6000
	s_mov_b32 s54, 0
	v_mov_b64_e32 v[0:1], 0
	v_mov_b64_e32 v[2:3], 0
	v_mov_b64_e32 v[4:5], 0
	v_mov_b64_e32 v[6:7], 0
	v_mov_b64_e32 v[8:9], 0
	v_mov_b64_e32 v[10:11], 0
	v_mov_b64_e32 v[12:13], 0
	v_mov_b64_e32 v[14:15], 0
	v_mov_b64_e32 v[16:17], 0
	v_mov_b64_e32 v[18:19], 0
	v_mov_b64_e32 v[20:21], 0
	v_mov_b64_e32 v[22:23], 0
	v_mov_b64_e32 v[24:25], 0
	v_mov_b64_e32 v[26:27], 0
	v_mov_b64_e32 v[28:29], 0
	v_mov_b64_e32 v[30:31], 0
	v_mov_b64_e32 v[218:219], 0
	v_mov_b64_e32 v[220:221], 0
	v_mov_b64_e32 v[222:223], 0
	v_mov_b64_e32 v[224:225], 0
	v_mov_b64_e32 v[226:227], 0
	v_mov_b64_e32 v[228:229], 0
	v_mov_b64_e32 v[230:231], 0
	v_mov_b64_e32 v[232:233], 0
	v_mov_b64_e32 v[234:235], 0
	v_mov_b64_e32 v[236:237], 0
	s_barrier
	s_waitcnt vmcnt(7)
	ds_write_b128 v238, v[136:139]
	s_waitcnt vmcnt(6)
	ds_write_b64 v239, v[208:209]
	s_waitcnt vmcnt(5)
	ds_write_b128 v238, v[140:143] offset:13312
	s_waitcnt vmcnt(4)
	ds_write_b64 v239, v[210:211] offset:13312
	s_waitcnt vmcnt(3)
	ds_write_b128 v241, v[144:147]
	s_waitcnt lgkmcnt(0)
	s_barrier
	ds_read_b128 v[136:139], v243 offset:0
	ds_read_b128 v[140:143], v243 offset:6656
	ds_read_b128 v[144:147], v243 offset:32
	ds_read_b128 v[148:151], v243 offset:6688
	s_waitcnt lgkmcnt(3)
	v_mfma_f32_32x32x16_bf16 v[32:47], v[136:139], v[112:115], 0
	ds_read_b128 v[136:139], v243 offset:64
	s_waitcnt lgkmcnt(3)
	v_mfma_f32_32x32x16_bf16 v[48:63], v[140:143], v[112:115], 0
	ds_read_b128 v[140:143], v243 offset:6720
	s_waitcnt lgkmcnt(3)
	v_mfma_f32_32x32x16_bf16 v[32:47], v[144:147], v[116:119], v[32:47]
	ds_read_b128 v[144:147], v243 offset:96
	s_waitcnt lgkmcnt(3)
	v_mfma_f32_32x32x16_bf16 v[48:63], v[148:151], v[116:119], v[48:63]
	ds_read_b128 v[148:151], v243 offset:6752
	s_waitcnt lgkmcnt(3)
	v_mfma_f32_32x32x16_bf16 v[32:47], v[136:139], v[120:123], v[32:47]
	ds_read_b128 v[136:139], v243 offset:128
	s_waitcnt lgkmcnt(3)
	v_mfma_f32_32x32x16_bf16 v[48:63], v[140:143], v[120:123], v[48:63]
	ds_read_b128 v[140:143], v243 offset:6784
	s_waitcnt lgkmcnt(3)
	v_mfma_f32_32x32x16_bf16 v[32:47], v[144:147], v[124:127], v[32:47]
	ds_read_b128 v[144:147], v243 offset:160
	s_waitcnt lgkmcnt(3)
	v_mfma_f32_32x32x16_bf16 v[48:63], v[148:151], v[124:127], v[48:63]
	ds_read_b128 v[148:151], v243 offset:6816
	s_waitcnt lgkmcnt(3)
	v_mfma_f32_32x32x16_bf16 v[32:47], v[136:139], v[128:131], v[32:47]
	s_waitcnt lgkmcnt(2)
	v_mfma_f32_32x32x16_bf16 v[48:63], v[140:143], v[128:131], v[48:63]
	s_waitcnt lgkmcnt(1)
	v_mfma_f32_32x32x16_bf16 v[32:47], v[144:147], v[132:135], v[32:47]
	s_waitcnt lgkmcnt(0)
	v_mfma_f32_32x32x16_bf16 v[48:63], v[148:151], v[132:135], v[48:63]
	s_waitcnt lgkmcnt(0)
	s_nop 7
	s_barrier
	ds_read_b128 v[136:139], v243 offset:13312
	ds_read_b128 v[140:143], v243 offset:19968
	ds_read_b128 v[144:147], v243 offset:13344
	ds_read_b128 v[148:151], v243 offset:20000
	v_max3_f32 v168, v32, v33, v34
	v_max3_f32 v170, v48, v49, v50
	v_max3_f32 v168, v168, v35, v36
	v_max3_f32 v170, v170, v51, v52
	v_max3_f32 v168, v168, v37, v38
	v_max3_f32 v170, v170, v53, v54
	v_max3_f32 v168, v168, v39, v40
	v_max3_f32 v170, v170, v55, v56
	v_max3_f32 v168, v168, v41, v42
	v_max3_f32 v170, v170, v57, v58
	v_max3_f32 v168, v168, v43, v44
	v_max3_f32 v170, v170, v59, v60
	v_max3_f32 v168, v168, v45, v46
	v_max3_f32 v170, v170, v61, v62
	v_max3_f32 v168, v168, v170, v47
	v_max_f32_e32 v168, v168, v63
	v_mov_b32_e32 v170, v168
	s_nop 1
	v_permlane32_swap_b32_e32 v168, v170
	v_max_f32_e32 v168, v168, v170
	v_mov_b32_e32 v170, v168
	v_sub_f32_e32 v218, v218, v170
	v_sub_f32_e32 v219, v219, v170
	v_sub_f32_e32 v220, v220, v170
	v_sub_f32_e32 v221, v221, v170
	v_sub_f32_e32 v222, v222, v170
	v_sub_f32_e32 v223, v223, v170
	v_sub_f32_e32 v224, v224, v170
	v_sub_f32_e32 v225, v225, v170
	v_sub_f32_e32 v226, v226, v170
	v_sub_f32_e32 v227, v227, v170
	v_sub_f32_e32 v228, v228, v170
	v_sub_f32_e32 v229, v229, v170
	v_sub_f32_e32 v230, v230, v170
	v_sub_f32_e32 v231, v231, v170
	v_sub_f32_e32 v232, v232, v170
	v_sub_f32_e32 v233, v233, v170
	v_sub_f32_e32 v32, v32, v170
	v_sub_f32_e32 v33, v33, v170
	v_sub_f32_e32 v34, v34, v170
	v_sub_f32_e32 v35, v35, v170
	v_sub_f32_e32 v36, v36, v170
	v_sub_f32_e32 v37, v37, v170
	v_sub_f32_e32 v38, v38, v170
	v_sub_f32_e32 v39, v39, v170
	v_sub_f32_e32 v40, v40, v170
	v_sub_f32_e32 v41, v41, v170
	v_sub_f32_e32 v42, v42, v170
	v_sub_f32_e32 v43, v43, v170
	v_sub_f32_e32 v44, v44, v170
	v_sub_f32_e32 v45, v45, v170
	v_sub_f32_e32 v46, v46, v170
	v_sub_f32_e32 v47, v47, v170
	v_sub_f32_e32 v48, v48, v170
	v_sub_f32_e32 v49, v49, v170
	v_sub_f32_e32 v50, v50, v170
	v_sub_f32_e32 v51, v51, v170
	v_sub_f32_e32 v52, v52, v170
	v_sub_f32_e32 v53, v53, v170
	v_sub_f32_e32 v54, v54, v170
	v_sub_f32_e32 v55, v55, v170
	v_sub_f32_e32 v56, v56, v170
	v_sub_f32_e32 v57, v57, v170
	v_sub_f32_e32 v58, v58, v170
	v_sub_f32_e32 v59, v59, v170
	v_sub_f32_e32 v60, v60, v170
	v_sub_f32_e32 v61, v61, v170
	v_sub_f32_e32 v62, v62, v170
	v_sub_f32_e32 v63, v63, v170
	s_waitcnt lgkmcnt(3)
	v_mfma_f32_32x32x16_bf16 v[64:79], v[136:139], v[112:115], v[218:233]
	v_exp_f32_e32 v32, v32
	v_exp_f32_e32 v48, v48
	v_exp_f32_e32 v33, v33
	v_exp_f32_e32 v49, v49
	v_exp_f32_e32 v34, v34
	ds_read_b128 v[136:139], v243 offset:13376
	s_mov_b32 s55, s52
	s_mov_b32 s52, s53
	s_mov_b32 s53, s54
	s_mov_b32 s54, s55
	s_mov_b32 s9, 0
	s_waitcnt lgkmcnt(3)
	v_mfma_f32_32x32x16_bf16 v[80:95], v[140:143], v[112:115], v[218:233]
	v_exp_f32_e32 v50, v50
	v_cvt_pk_bf16_f32 v96, v32, v33
	v_cvt_pk_bf16_f32 v104, v48, v49
	v_exp_f32_e32 v35, v35
	v_exp_f32_e32 v51, v51
	ds_read_b128 v[140:143], v243 offset:20032
	global_load_dwordx4 v[208:211], v167, s[2:3]
	global_load_dwordx2 v[216:217], v165, s[10:11]
	global_load_dwordx4 v[212:215], v167, s[4:5]
	s_add_u32 s2, s2, 0x2000
	s_addc_u32 s3, s3, 0
	s_add_u32 s10, s10, 0x1000
	s_addc_u32 s11, s11, 0
	s_add_u32 s4, s4, 0x2000
	s_addc_u32 s5, s5, 0
	v_add_u32_e32 v163, s53, v240
	v_add_u32_e32 v164, s54, v241
	s_waitcnt lgkmcnt(3)
	v_mfma_f32_32x32x16_bf16 v[64:79], v[144:147], v[116:119], v[64:79]
	v_exp_f32_e32 v36, v36
	v_exp_f32_e32 v52, v52
	v_cvt_pk_bf16_f32 v97, v34, v35
	v_cvt_pk_bf16_f32 v105, v50, v51
	v_exp_f32_e32 v37, v37
	ds_read_b128 v[144:147], v243 offset:13408
	s_waitcnt lgkmcnt(3)
	v_mfma_f32_32x32x16_bf16 v[80:95], v[148:151], v[116:119], v[80:95]
	v_exp_f32_e32 v53, v53
	v_exp_f32_e32 v38, v38
	v_exp_f32_e32 v54, v54
	v_cvt_pk_bf16_f32 v98, v36, v37
	ds_read_b128 v[148:151], v243 offset:20064
	s_waitcnt lgkmcnt(3)
	v_mfma_f32_32x32x16_bf16 v[64:79], v[136:139], v[120:123], v[64:79]
	v_cvt_pk_bf16_f32 v106, v52, v53
	v_exp_f32_e32 v39, v39
	v_exp_f32_e32 v55, v55
	v_exp_f32_e32 v40, v40
	v_exp_f32_e32 v56, v56
	ds_read_b128 v[136:139], v243 offset:13440
	s_waitcnt lgkmcnt(3)
	v_mfma_f32_32x32x16_bf16 v[80:95], v[140:143], v[120:123], v[80:95]
	v_cvt_pk_bf16_f32 v99, v38, v39
	v_cvt_pk_bf16_f32 v107, v54, v55
	v_exp_f32_e32 v41, v41
	v_exp_f32_e32 v57, v57
	v_exp_f32_e32 v42, v42
	ds_read_b128 v[140:143], v243 offset:20096
	s_waitcnt lgkmcnt(3)
	v_mfma_f32_32x32x16_bf16 v[64:79], v[144:147], v[124:127], v[64:79]
	v_exp_f32_e32 v58, v58
	v_cvt_pk_bf16_f32 v100, v40, v41
	v_cvt_pk_bf16_f32 v108, v56, v57
	v_exp_f32_e32 v43, v43
	v_exp_f32_e32 v59, v59
	ds_read_b128 v[144:147], v243 offset:13472
	ds_read_b64_tr_b16 v[176:177], v163 offset:0
	ds_read_b64_tr_b16 v[178:179], v163 offset:1536
	s_waitcnt vmcnt(5)
	ds_write_b128 v238, v[152:155]
	s_waitcnt vmcnt(4)
	ds_write_b64 v239, v[160:161]
	s_waitcnt vmcnt(3)
	ds_write_b128 v164, v[156:159]
	s_waitcnt lgkmcnt(8)
	v_mfma_f32_32x32x16_bf16 v[80:95], v[148:151], v[124:127], v[80:95]
	v_exp_f32_e32 v44, v44
	v_exp_f32_e32 v60, v60
	v_cvt_pk_bf16_f32 v101, v42, v43
	v_cvt_pk_bf16_f32 v109, v58, v59
	v_exp_f32_e32 v45, v45
	ds_read_b128 v[148:151], v243 offset:20128
	ds_read_b64_tr_b16 v[180:181], v163 offset:64
	ds_read_b64_tr_b16 v[182:183], v163 offset:1600
	s_waitcnt lgkmcnt(10)
	v_mfma_f32_32x32x16_bf16 v[64:79], v[136:139], v[128:131], v[64:79]
	v_exp_f32_e32 v61, v61
	v_exp_f32_e32 v46, v46
	v_exp_f32_e32 v62, v62
	v_cvt_pk_bf16_f32 v102, v44, v45
	v_cvt_pk_bf16_f32 v110, v60, v61
	ds_read_b64_tr_b16 v[184:185], v163 offset:6144
	ds_read_b64_tr_b16 v[186:187], v163 offset:7680
	s_waitcnt lgkmcnt(11)
	v_mfma_f32_32x32x16_bf16 v[80:95], v[140:143], v[128:131], v[80:95]
	v_exp_f32_e32 v47, v47
	v_exp_f32_e32 v63, v63
	v_cvt_pk_bf16_f32 v103, v46, v47
	v_cvt_pk_bf16_f32 v111, v62, v63
	ds_read_b64_tr_b16 v[188:189], v163 offset:6208
	ds_read_b64_tr_b16 v[190:191], v163 offset:7744
	s_waitcnt lgkmcnt(12)
	v_mfma_f32_32x32x16_bf16 v[64:79], v[144:147], v[132:135], v[64:79]
	s_waitcnt lgkmcnt(6)
	v_mfma_f32_32x32x16_bf16 v[80:95], v[148:151], v[132:135], v[80:95]
	s_nop 13
	s_waitcnt lgkmcnt(0)
	s_barrier
	s_cmp_eq_u32 s7, 0
	s_cbranch_scc1 .Lamla_tail

; #define AT_GLOADK(k0) do { kreg = *(const u32x4*)(Kb + (size_t)((k0) + (tid >> 3)) * 64 + (tid & 7) * 8); \
;             if (MLA) preg = *(const u32x2*)(Pb + (size_t)((k0) + (tid >> 3)) * 32 + (tid & 7) * 4); } while (0)
; #define AT_GLOADV(k0) do { vreg = *(const u32x4*)(Vb + (size_t)((k0) + (tid >> 3)) * 64 + (tid & 7) * 8); } while (0)
; #define AT_WRITEK(buf) do { *(LAS u32x4*)(lds + (buf) * KBUF + (tid >> 3) * KSTR + (tid & 7) * 16) = kreg; \
;             if (MLA) *(LAS u32x2*)(lds + (buf) * KBUF + (tid >> 3) * KSTR + 128 + (tid & 7) * 8) = preg; } while (0)
; #define AT_WRITEV(buf) do { *(LAS u32x4*)(lds + 2 * KBUF + (buf) * VBUF + (tid >> 3) * VSTR + (tid & 7) * 16) = vreg; } while (0)
; template <bool MLA>
; DI void attn_phase(const int TID, const int BID, LAS unsigned char* lds, const Params& p, bool need_ctx) {
;     ...
;         f32x16 o0, o1, sa0, sa1, sb0, sb1;
; #pragma unroll
;         for (int j = 0; j < 16; ++j) { o0[j] = 0.f; o1[j] = 0.f; }
;         float mrun = -1e30f, lsum = 0.f;
;         if (wid >= 4) __builtin_amdgcn_s_setprio(1);
;         const int ntile = nk >> 6;
;         AT_GLOADK(0); AT_GLOADV(0); AT_WRITEK(0); AT_WRITEV(0);
;         AT_GLOADK(64); AT_WRITEK(1);
;         __syncthreads();
;         AT_QK(sa0, sa1, 0);
;         __syncthreads();
.Lagqa_item:
	s_mov_b32 s52, 0x3000
	s_mov_b32 s53, 0x6000
	s_mov_b32 s54, 0
	v_mov_b64_e32 v[0:1], 0
	v_mov_b64_e32 v[2:3], 0
	v_mov_b64_e32 v[4:5], 0
	v_mov_b64_e32 v[6:7], 0
	v_mov_b64_e32 v[8:9], 0
	v_mov_b64_e32 v[10:11], 0
	v_mov_b64_e32 v[12:13], 0
	v_mov_b64_e32 v[14:15], 0
	v_mov_b64_e32 v[16:17], 0
	v_mov_b64_e32 v[18:19], 0
	v_mov_b64_e32 v[20:21], 0
	v_mov_b64_e32 v[22:23], 0
	v_mov_b64_e32 v[24:25], 0
	v_mov_b64_e32 v[26:27], 0
	v_mov_b64_e32 v[28:29], 0
	v_mov_b64_e32 v[30:31], 0
	v_mov_b64_e32 v[218:219], 0
	v_mov_b64_e32 v[220:221], 0
	v_mov_b64_e32 v[222:223], 0
	v_mov_b64_e32 v[224:225], 0
	v_mov_b64_e32 v[226:227], 0
	v_mov_b64_e32 v[228:229], 0
	v_mov_b64_e32 v[230:231], 0
	v_mov_b64_e32 v[232:233], 0
	v_mov_b64_e32 v[234:235], 0
	v_mov_b64_e32 v[236:237], 0
	s_barrier
	s_waitcnt vmcnt(4)
	ds_write_b128 v238, v[136:139]
	s_waitcnt vmcnt(3)
	ds_write_b128 v238, v[140:143] offset:9216
	s_waitcnt vmcnt(2)
	ds_write_b128 v241, v[144:147]
	s_waitcnt lgkmcnt(0)
	s_barrier
	ds_read_b128 v[136:139], v243 offset:0
	ds_read_b128 v[140:143], v243 offset:4608
	ds_read_b128 v[144:147], v243 offset:32
	ds_read_b128 v[148:151], v243 offset:4640
	s_waitcnt lgkmcnt(3)
	v_mfma_f32_32x32x16_bf16 v[32:47], v[136:139], v[112:115], 0
	ds_read_b128 v[136:139], v243 offset:64
	s_waitcnt lgkmcnt(3)
	v_mfma_f32_32x32x16_bf16 v[48:63], v[140:143], v[112:115], 0
	ds_read_b128 v[140:143], v243 offset:4672
	s_waitcnt lgkmcnt(3)
	v_mfma_f32_32x32x16_bf16 v[32:47], v[144:147], v[116:119], v[32:47]
	ds_read_b128 v[144:147], v243 offset:96
	s_waitcnt lgkmcnt(3)
	v_mfma_f32_32x32x16_bf16 v[48:63], v[148:151], v[116:119], v[48:63]
	ds_read_b128 v[148:151], v243 offset:4704
	s_waitcnt lgkmcnt(3)
	v_mfma_f32_32x32x16_bf16 v[32:47], v[136:139], v[120:123], v[32:47]
	s_waitcnt lgkmcnt(2)
	v_mfma_f32_32x32x16_bf16 v[48:63], v[140:143], v[120:123], v[48:63]
	s_waitcnt lgkmcnt(1)
	v_mfma_f32_32x32x16_bf16 v[32:47], v[144:147], v[124:127], v[32:47]
	s_waitcnt lgkmcnt(0)
	v_mfma_f32_32x32x16_bf16 v[48:63], v[148:151], v[124:127], v[48:63]
	s_waitcnt lgkmcnt(0)
	s_nop 7
	s_barrier
	ds_read_b128 v[136:139], v243 offset:9216
	ds_read_b128 v[140:143], v243 offset:13824
	ds_read_b128 v[144:147], v243 offset:9248
	ds_read_b128 v[148:151], v243 offset:13856
	v_max3_f32 v168, v32, v33, v34
	v_max3_f32 v170, v48, v49, v50
	v_max3_f32 v168, v168, v35, v36
	v_max3_f32 v170, v170, v51, v52
	v_max3_f32 v168, v168, v37, v38
	v_max3_f32 v170, v170, v53, v54
	v_max3_f32 v168, v168, v39, v40
	v_max3_f32 v170, v170, v55, v56
	v_max3_f32 v168, v168, v41, v42
	v_max3_f32 v170, v170, v57, v58
	v_max3_f32 v168, v168, v43, v44
	v_max3_f32 v170, v170, v59, v60
	v_max3_f32 v168, v168, v45, v46
	v_max3_f32 v170, v170, v61, v62
	v_max3_f32 v168, v168, v170, v47
	v_max_f32_e32 v168, v168, v63
	v_mov_b32_e32 v170, v168
	s_nop 1
	v_permlane32_swap_b32_e32 v168, v170
	v_max_f32_e32 v168, v168, v170
	v_mov_b32_e32 v170, v168
	v_sub_f32_e32 v218, v218, v170
	v_sub_f32_e32 v219, v219, v170
	v_sub_f32_e32 v220, v220, v170
	v_sub_f32_e32 v221, v221, v170
	v_sub_f32_e32 v222, v222, v170
	v_sub_f32_e32 v223, v223, v170
	v_sub_f32_e32 v224, v224, v170
	v_sub_f32_e32 v225, v225, v170
	v_sub_f32_e32 v226, v226, v170
	v_sub_f32_e32 v227, v227, v170
	v_sub_f32_e32 v228, v228, v170
	v_sub_f32_e32 v229, v229, v170
	v_sub_f32_e32 v230, v230, v170
	v_sub_f32_e32 v231, v231, v170
	v_sub_f32_e32 v232, v232, v170
	v_sub_f32_e32 v233, v233, v170
	v_sub_f32_e32 v32, v32, v170
	v_sub_f32_e32 v33, v33, v170
	v_sub_f32_e32 v34, v34, v170
	v_sub_f32_e32 v35, v35, v170
	v_sub_f32_e32 v36, v36, v170
	v_sub_f32_e32 v37, v37, v170
	v_sub_f32_e32 v38, v38, v170
	v_sub_f32_e32 v39, v39, v170
	v_sub_f32_e32 v40, v40, v170
	v_sub_f32_e32 v41, v41, v170
	v_sub_f32_e32 v42, v42, v170
	v_sub_f32_e32 v43, v43, v170
	v_sub_f32_e32 v44, v44, v170
	v_sub_f32_e32 v45, v45, v170
	v_sub_f32_e32 v46, v46, v170
	v_sub_f32_e32 v47, v47, v170
	v_sub_f32_e32 v48, v48, v170
	v_sub_f32_e32 v49, v49, v170
	v_sub_f32_e32 v50, v50, v170
	v_sub_f32_e32 v51, v51, v170
	v_sub_f32_e32 v52, v52, v170
	v_sub_f32_e32 v53, v53, v170
	v_sub_f32_e32 v54, v54, v170
	v_sub_f32_e32 v55, v55, v170
	v_sub_f32_e32 v56, v56, v170
	v_sub_f32_e32 v57, v57, v170
	v_sub_f32_e32 v58, v58, v170
	v_sub_f32_e32 v59, v59, v170
	v_sub_f32_e32 v60, v60, v170
	v_sub_f32_e32 v61, v61, v170
	v_sub_f32_e32 v62, v62, v170
	v_sub_f32_e32 v63, v63, v170
	s_waitcnt lgkmcnt(3)
	v_mfma_f32_32x32x16_bf16 v[64:79], v[136:139], v[112:115], v[218:233]
	v_exp_f32_e32 v32, v32
	v_exp_f32_e32 v48, v48
	v_exp_f32_e32 v33, v33
	v_exp_f32_e32 v49, v49
	v_exp_f32_e32 v34, v34
	v_exp_f32_e32 v50, v50
	v_cvt_pk_bf16_f32 v96, v32, v33
	ds_read_b128 v[136:139], v243 offset:9280
	s_mov_b32 s55, s52
	s_mov_b32 s52, s53
	s_mov_b32 s53, s54
	s_mov_b32 s54, s55
	s_mov_b32 s9, 0
	s_waitcnt lgkmcnt(3)
	v_mfma_f32_32x32x16_bf16 v[80:95], v[140:143], v[112:115], v[218:233]
	v_cvt_pk_bf16_f32 v104, v48, v49
	v_exp_f32_e32 v35, v35
	v_exp_f32_e32 v51, v51
	v_exp_f32_e32 v36, v36
	v_exp_f32_e32 v52, v52
	v_cvt_pk_bf16_f32 v97, v34, v35
	v_cvt_pk_bf16_f32 v105, v50, v51
	v_exp_f32_e32 v37, v37
	ds_read_b128 v[140:143], v243 offset:13888
	global_load_dwordx4 v[208:211], v167, s[2:3]
	global_load_dwordx4 v[212:215], v167, s[4:5]
	s_add_u32 s2, s2, 0x2000
	s_addc_u32 s3, s3, 0
	s_add_u32 s4, s4, 0x2000
	s_addc_u32 s5, s5, 0
	v_add_u32_e32 v163, s53, v240
	v_add_u32_e32 v164, s54, v241
	s_waitcnt lgkmcnt(3)
	v_mfma_f32_32x32x16_bf16 v[64:79], v[144:147], v[116:119], v[64:79]
	v_exp_f32_e32 v53, v53
	v_exp_f32_e32 v38, v38
	v_exp_f32_e32 v54, v54
	v_cvt_pk_bf16_f32 v98, v36, v37
	v_cvt_pk_bf16_f32 v106, v52, v53
	v_exp_f32_e32 v39, v39
	v_exp_f32_e32 v55, v55
	ds_read_b128 v[144:147], v243 offset:9312
	ds_read_b64_tr_b16 v[176:177], v163 offset:0
	ds_read_b64_tr_b16 v[178:179], v163 offset:1536
	s_waitcnt lgkmcnt(5)
	v_mfma_f32_32x32x16_bf16 v[80:95], v[148:151], v[116:119], v[80:95]
	v_exp_f32_e32 v40, v40
	v_exp_f32_e32 v56, v56
	v_cvt_pk_bf16_f32 v99, v38, v39
	v_cvt_pk_bf16_f32 v107, v54, v55
	v_exp_f32_e32 v41, v41
	v_exp_f32_e32 v57, v57
	v_exp_f32_e32 v42, v42
	ds_read_b128 v[148:151], v243 offset:13920
	ds_read_b64_tr_b16 v[180:181], v163 offset:64
	ds_read_b64_tr_b16 v[182:183], v163 offset:1600
	s_waitcnt lgkmcnt(7)
	v_mfma_f32_32x32x16_bf16 v[64:79], v[136:139], v[120:123], v[64:79]
	v_exp_f32_e32 v58, v58
	v_cvt_pk_bf16_f32 v100, v40, v41
	v_cvt_pk_bf16_f32 v108, v56, v57
	v_exp_f32_e32 v43, v43
	v_exp_f32_e32 v59, v59
	v_exp_f32_e32 v44, v44
	v_exp_f32_e32 v60, v60
	ds_read_b64_tr_b16 v[184:185], v163 offset:6144
	ds_read_b64_tr_b16 v[186:187], v163 offset:7680
	s_waitcnt vmcnt(3)
	ds_write_b128 v238, v[152:155]
	s_waitcnt vmcnt(2)
	ds_write_b128 v164, v[156:159]
	s_waitcnt lgkmcnt(10)
	v_mfma_f32_32x32x16_bf16 v[80:95], v[140:143], v[120:123], v[80:95]
	v_cvt_pk_bf16_f32 v101, v42, v43
	v_cvt_pk_bf16_f32 v109, v58, v59
	v_exp_f32_e32 v45, v45
	v_exp_f32_e32 v61, v61
	v_exp_f32_e32 v46, v46
	v_exp_f32_e32 v62, v62
	v_cvt_pk_bf16_f32 v102, v44, v45
	v_cvt_pk_bf16_f32 v110, v60, v61
	ds_read_b64_tr_b16 v[188:189], v163 offset:6208
	ds_read_b64_tr_b16 v[190:191], v163 offset:7744
	s_waitcnt lgkmcnt(11)
	v_mfma_f32_32x32x16_bf16 v[64:79], v[144:147], v[124:127], v[64:79]
	v_exp_f32_e32 v47, v47
	v_exp_f32_e32 v63, v63
	v_cvt_pk_bf16_f32 v103, v46, v47
	v_cvt_pk_bf16_f32 v111, v62, v63
	s_waitcnt lgkmcnt(8)
	v_mfma_f32_32x32x16_bf16 v[80:95], v[148:151], v[124:127], v[80:95]
	s_nop 13
	s_waitcnt lgkmcnt(2)
	s_waitcnt lgkmcnt(0)
	s_barrier
	s_cmp_eq_u32 s7, 0
	s_cbranch_scc1 .Lagqa_tail
